# accumulator zeroing with v_pk_mov_b32 (two registers per full-rate op) on top of the v072 combination
# speedup vs baseline: 1.0036x; 1.0014x over previous
; template <class Epi, class Sched, bool ALIGN_EPI = false, bool SP2 = false>
; __device__ __forceinline__ void gemm_phase(PG8_LAS unsigned char* lds, const Gemm g, const Sched& S, const Epi& E, const int wave_) {
;     ...
;         const bool has_next = S.next(ui + 1, nxt);
;         const char* nA = has_next ? (const char*)g.A + (size_t)nxt.pm * tstep : cA; const char* nB = has_next ? (const char*)g.Bt + (size_t)nxt.pn * tstep : cB;
;     ...
;         for (int a = 0; a < 2; ++a)
; #pragma unroll
;             for (int b = 0; b < 2; ++b)
; #pragma unroll
;                 for (int m = 0; m < 4; ++m)
; #pragma unroll
;                     for (int n = 0; n < 2; ++n) acc[a][b][m][n] = (f32x4){0.f, 0.f, 0.f, 0.f};
;         cur = nxt; cA = nA; cB = nB; ++ui;
.LBB0_128:
	s_ashr_i32 s39, s38, 31
	s_lshl_b64 s[22:23], s[38:39], 20
	v_readlane_b32 s24, v248, 27
	v_readlane_b32 s25, v248, 28
	s_add_u32 s40, s24, s22
	s_addc_u32 s41, s25, s23
	s_and_b64 s[22:23], s[16:17], exec
	s_cselect_b32 s19, s41, s47
	s_cselect_b32 s39, s40, s46
	s_ashr_i32 s37, s36, 31
	s_lshl_b64 s[22:23], s[36:37], 20
	v_readlane_b32 s24, v248, 25
	v_readlane_b32 s25, v248, 26
	s_add_u32 s42, s24, s22
	s_addc_u32 s43, s25, s23
	s_and_b64 s[22:23], s[16:17], exec
	s_cselect_b32 s37, s43, s49
	s_cselect_b32 vcc_lo, s42, s48
	s_add_u32 s46, s46, 0x80080
	s_addc_u32 s47, s47, 0
	s_add_u32 vcc_hi, s48, 0x100
	v_mov_b32_e32 v0, 0
	s_addc_u32 s97, s49, 0
	s_mov_b32 s22, -2
	v_mov_b32_e32 v1, 0
	v_pk_mov_b32 v[2:3], 0, 0
	v_pk_mov_b32 v[4:5], 0, 0
	v_pk_mov_b32 v[6:7], 0, 0
	v_pk_mov_b32 v[8:9], 0, 0
	v_pk_mov_b32 v[10:11], 0, 0
	v_pk_mov_b32 v[12:13], 0, 0
	v_pk_mov_b32 v[14:15], 0, 0
	v_pk_mov_b32 v[16:17], 0, 0
	v_pk_mov_b32 v[18:19], 0, 0
	v_pk_mov_b32 v[20:21], 0, 0
	v_pk_mov_b32 v[22:23], 0, 0
	v_pk_mov_b32 v[24:25], 0, 0
	v_pk_mov_b32 v[26:27], 0, 0
	v_pk_mov_b32 v[28:29], 0, 0
	v_pk_mov_b32 v[30:31], 0, 0
	v_pk_mov_b32 v[32:33], 0, 0
	v_pk_mov_b32 v[34:35], 0, 0
	v_pk_mov_b32 v[36:37], 0, 0
	v_pk_mov_b32 v[38:39], 0, 0
	v_pk_mov_b32 v[40:41], 0, 0
	v_pk_mov_b32 v[42:43], 0, 0
	v_pk_mov_b32 v[44:45], 0, 0
	v_pk_mov_b32 v[46:47], 0, 0
	v_pk_mov_b32 v[48:49], 0, 0
	v_pk_mov_b32 v[50:51], 0, 0
	v_pk_mov_b32 v[52:53], 0, 0
	v_pk_mov_b32 v[54:55], 0, 0
	v_pk_mov_b32 v[56:57], 0, 0
	v_pk_mov_b32 v[58:59], 0, 0
	v_pk_mov_b32 v[60:61], 0, 0
	v_pk_mov_b32 v[62:63], 0, 0
	v_pk_mov_b32 v[64:65], 0, 0
	v_pk_mov_b32 v[66:67], 0, 0
	v_pk_mov_b32 v[68:69], 0, 0
	v_pk_mov_b32 v[70:71], 0, 0
	v_pk_mov_b32 v[72:73], 0, 0
	v_pk_mov_b32 v[74:75], 0, 0
	v_pk_mov_b32 v[76:77], 0, 0
	v_pk_mov_b32 v[78:79], 0, 0
	v_pk_mov_b32 v[80:81], 0, 0
	v_pk_mov_b32 v[82:83], 0, 0
	v_pk_mov_b32 v[84:85], 0, 0
	v_pk_mov_b32 v[86:87], 0, 0
	v_pk_mov_b32 v[88:89], 0, 0
	v_pk_mov_b32 v[90:91], 0, 0
	v_pk_mov_b32 v[92:93], 0, 0
	v_pk_mov_b32 v[94:95], 0, 0
	v_pk_mov_b32 v[96:97], 0, 0
	v_pk_mov_b32 v[98:99], 0, 0
	v_pk_mov_b32 v[100:101], 0, 0
	v_pk_mov_b32 v[102:103], 0, 0
	v_pk_mov_b32 v[104:105], 0, 0
	v_pk_mov_b32 v[106:107], 0, 0
	v_pk_mov_b32 v[108:109], 0, 0
	v_pk_mov_b32 v[110:111], 0, 0
	v_pk_mov_b32 v[112:113], 0, 0
	v_pk_mov_b32 v[114:115], 0, 0
	v_pk_mov_b32 v[116:117], 0, 0
	v_pk_mov_b32 v[118:119], 0, 0
	v_pk_mov_b32 v[120:121], 0, 0
	v_pk_mov_b32 v[122:123], 0, 0
	v_pk_mov_b32 v[124:125], 0, 0
	v_pk_mov_b32 v[126:127], 0, 0

; template <class Epi, class Sched, bool ALIGN_EPI = false, bool SP2 = false>
; __device__ __forceinline__ void gemm_phase(PG8_LAS unsigned char* lds, const Gemm g, const Sched& S, const Epi& E, const int wave_) {
;     ...
;         const bool has_next = S.next(ui + 1, nxt);
;         const char* nA = has_next ? (const char*)g.A + (size_t)nxt.pm * tstep : cA; const char* nB = has_next ? (const char*)g.Bt + (size_t)nxt.pn * tstep : cB;
;     ...
;         for (int a = 0; a < 2; ++a)
; #pragma unroll
;             for (int b = 0; b < 2; ++b)
; #pragma unroll
;                 for (int m = 0; m < 4; ++m)
; #pragma unroll
;                     for (int n = 0; n < 2; ++n) acc[a][b][m][n] = (f32x4){0.f, 0.f, 0.f, 0.f};
;         cur = nxt; cA = nA; cB = nB; ++ui;
.LBB0_401:
	s_ashr_i32 s19, s18, 31
	s_lshl_b64 s[20:21], s[18:19], 21
	v_readlane_b32 s22, v248, 25
	v_readlane_b32 s23, v248, 26
	s_add_u32 s20, s22, s20
	s_addc_u32 s21, s23, s21
	s_and_b64 s[22:23], s[4:5], exec
	s_cselect_b32 s19, s21, s29
	s_cselect_b32 s25, s20, s28
	s_ashr_i32 s17, s16, 31
	s_lshl_b64 s[22:23], s[16:17], 21
	v_readlane_b32 s34, v248, 29
	v_readlane_b32 s35, v248, 30
	s_add_u32 s22, s34, s22
	s_addc_u32 s23, s35, s23
	s_and_b64 s[34:35], s[4:5], exec
	s_cselect_b32 s17, s23, s31
	s_cselect_b32 s50, s22, s30
	s_add_u32 s28, s28, 0x100080
	s_addc_u32 s29, s29, 0
	s_add_u32 s51, s30, 0x100
	v_mov_b32_e32 v0, 0
	s_addc_u32 s52, s31, 0
	s_mov_b32 s53, -2
	s_waitcnt lgkmcnt(0)
	v_mov_b32_e32 v1, 0
	v_pk_mov_b32 v[2:3], 0, 0
	v_pk_mov_b32 v[4:5], 0, 0
	v_pk_mov_b32 v[6:7], 0, 0
	v_pk_mov_b32 v[8:9], 0, 0
	v_pk_mov_b32 v[10:11], 0, 0
	v_pk_mov_b32 v[12:13], 0, 0
	v_pk_mov_b32 v[14:15], 0, 0
	v_pk_mov_b32 v[16:17], 0, 0
	v_pk_mov_b32 v[18:19], 0, 0
	v_pk_mov_b32 v[20:21], 0, 0
	v_pk_mov_b32 v[22:23], 0, 0
	v_pk_mov_b32 v[24:25], 0, 0
	v_pk_mov_b32 v[26:27], 0, 0
	v_pk_mov_b32 v[28:29], 0, 0
	v_pk_mov_b32 v[30:31], 0, 0
	v_pk_mov_b32 v[32:33], 0, 0
	v_pk_mov_b32 v[34:35], 0, 0
	v_pk_mov_b32 v[36:37], 0, 0
	v_pk_mov_b32 v[38:39], 0, 0
	v_pk_mov_b32 v[40:41], 0, 0
	v_pk_mov_b32 v[42:43], 0, 0
	v_pk_mov_b32 v[44:45], 0, 0
	v_pk_mov_b32 v[46:47], 0, 0
	v_pk_mov_b32 v[48:49], 0, 0
	v_pk_mov_b32 v[50:51], 0, 0
	v_pk_mov_b32 v[52:53], 0, 0
	v_pk_mov_b32 v[54:55], 0, 0
	v_pk_mov_b32 v[56:57], 0, 0
	v_pk_mov_b32 v[58:59], 0, 0
	v_pk_mov_b32 v[60:61], 0, 0
	v_pk_mov_b32 v[62:63], 0, 0
	v_pk_mov_b32 v[64:65], 0, 0
	v_pk_mov_b32 v[66:67], 0, 0
	v_pk_mov_b32 v[68:69], 0, 0
	v_pk_mov_b32 v[70:71], 0, 0
	v_pk_mov_b32 v[72:73], 0, 0
	v_pk_mov_b32 v[74:75], 0, 0
	v_pk_mov_b32 v[76:77], 0, 0
	v_pk_mov_b32 v[78:79], 0, 0
	v_pk_mov_b32 v[80:81], 0, 0
	v_pk_mov_b32 v[82:83], 0, 0
	v_pk_mov_b32 v[84:85], 0, 0
	v_pk_mov_b32 v[86:87], 0, 0
	v_pk_mov_b32 v[88:89], 0, 0
	v_pk_mov_b32 v[90:91], 0, 0
	v_pk_mov_b32 v[92:93], 0, 0
	v_pk_mov_b32 v[94:95], 0, 0
	v_pk_mov_b32 v[96:97], 0, 0
	v_pk_mov_b32 v[98:99], 0, 0
	v_pk_mov_b32 v[100:101], 0, 0
	v_pk_mov_b32 v[102:103], 0, 0
	v_pk_mov_b32 v[104:105], 0, 0
	v_pk_mov_b32 v[106:107], 0, 0
	v_pk_mov_b32 v[108:109], 0, 0
	v_pk_mov_b32 v[110:111], 0, 0
	v_pk_mov_b32 v[112:113], 0, 0
	v_pk_mov_b32 v[114:115], 0, 0
	v_pk_mov_b32 v[116:117], 0, 0
	v_pk_mov_b32 v[118:119], 0, 0
	v_pk_mov_b32 v[120:121], 0, 0
	v_pk_mov_b32 v[122:123], 0, 0
	v_pk_mov_b32 v[124:125], 0, 0
	v_pk_mov_b32 v[126:127], 0, 0

; template <class Epi, class Sched, bool ALIGN_EPI = false, bool SP2 = false>
; __device__ __forceinline__ void gemm_phase(PG8_LAS unsigned char* lds, const Gemm g, const Sched& S, const Epi& E, const int wave_) {
;     ...
;         for (int a = 0; a < 2; ++a)
; #pragma unroll
;             for (int b = 0; b < 2; ++b)
; #pragma unroll
;                 for (int m = 0; m < 4; ++m)
; #pragma unroll
;                     for (int n = 0; n < 2; ++n) acc[a][b][m][n] = (f32x4){0.f, 0.f, 0.f, 0.f};
;         cur = nxt; cA = nA; cB = nB; ++ui;
;     __device__ __forceinline__ void operator()(const f32x4 (&acc)[2][2][4][2], const Unit& u, int wr, int wc, int fr, int fq) const {
;     ...
;             for (int m = 0; m < 4; ++m) ssr[ai][m] = hss[row0 + ai * HALF + m * 16];
.LBB0_494:
	v_lshl_add_u32 v244, s4, 8, v153
	v_ashrrev_i32_e32 v245, 31, v244
	v_lshl_add_u64 v[246:247], v[244:245], 2, s[8:9]
	global_load_dword v236, v[246:247], off
	global_load_dword v237, v[246:247], off offset:64
	global_load_dword v238, v[246:247], off offset:128
	global_load_dword v239, v[246:247], off offset:192
	global_load_dword v240, v[246:247], off offset:512
	global_load_dword v241, v[246:247], off offset:576
	global_load_dword v242, v[246:247], off offset:640
	global_load_dword v243, v[246:247], off offset:704
	s_ashr_i32 s29, s28, 31
	s_lshl_b64 s[30:31], s[28:29], 20
	s_add_u32 s30, s38, s30
	s_addc_u32 s31, s39, s31
	s_and_b64 s[34:35], s[0:1], exec
	s_cselect_b32 s5, s31, s37
	s_cselect_b32 s7, s30, s36
	s_ashr_i32 s27, s26, 31
	s_lshl_b64 s[34:35], s[26:27], 20
	v_readlane_b32 s42, v248, 31
	v_readlane_b32 s43, v248, 32
	s_add_u32 s34, s42, s34
	s_addc_u32 s35, s43, s35
	s_and_b64 s[42:43], s[0:1], exec
	s_cselect_b32 s27, s35, s41
	s_cselect_b32 s29, s34, s40
	s_add_u32 s36, s36, 0x80080
	s_addc_u32 s37, s37, 0
	s_add_u32 s61, s40, 0x100
	v_mov_b32_e32 v0, 0
	s_addc_u32 s62, s41, 0
	s_mov_b32 s63, -2
	v_mov_b32_e32 v1, 0
	v_pk_mov_b32 v[2:3], 0, 0
	v_pk_mov_b32 v[4:5], 0, 0
	v_pk_mov_b32 v[6:7], 0, 0
	v_pk_mov_b32 v[8:9], 0, 0
	v_pk_mov_b32 v[10:11], 0, 0
	v_pk_mov_b32 v[12:13], 0, 0
	v_pk_mov_b32 v[14:15], 0, 0
	v_pk_mov_b32 v[16:17], 0, 0
	v_pk_mov_b32 v[18:19], 0, 0
	v_pk_mov_b32 v[20:21], 0, 0
	v_pk_mov_b32 v[22:23], 0, 0
	v_pk_mov_b32 v[24:25], 0, 0
	v_pk_mov_b32 v[26:27], 0, 0
	v_pk_mov_b32 v[28:29], 0, 0
	v_pk_mov_b32 v[30:31], 0, 0
	v_pk_mov_b32 v[32:33], 0, 0
	v_pk_mov_b32 v[34:35], 0, 0
	v_pk_mov_b32 v[36:37], 0, 0
	v_pk_mov_b32 v[38:39], 0, 0
	v_pk_mov_b32 v[40:41], 0, 0
	v_pk_mov_b32 v[42:43], 0, 0
	v_pk_mov_b32 v[44:45], 0, 0
	v_pk_mov_b32 v[46:47], 0, 0
	v_pk_mov_b32 v[48:49], 0, 0
	v_pk_mov_b32 v[50:51], 0, 0
	v_pk_mov_b32 v[52:53], 0, 0
	v_pk_mov_b32 v[54:55], 0, 0
	v_pk_mov_b32 v[56:57], 0, 0
	v_pk_mov_b32 v[58:59], 0, 0
	v_pk_mov_b32 v[60:61], 0, 0
	v_pk_mov_b32 v[62:63], 0, 0
	v_pk_mov_b32 v[64:65], 0, 0
	v_pk_mov_b32 v[66:67], 0, 0
	v_pk_mov_b32 v[68:69], 0, 0
	v_pk_mov_b32 v[70:71], 0, 0
	v_pk_mov_b32 v[72:73], 0, 0
	v_pk_mov_b32 v[74:75], 0, 0
	v_pk_mov_b32 v[76:77], 0, 0
	v_pk_mov_b32 v[78:79], 0, 0
	v_pk_mov_b32 v[80:81], 0, 0
	v_pk_mov_b32 v[82:83], 0, 0
	v_pk_mov_b32 v[84:85], 0, 0
	v_pk_mov_b32 v[86:87], 0, 0
	v_pk_mov_b32 v[88:89], 0, 0
	v_pk_mov_b32 v[90:91], 0, 0
	v_pk_mov_b32 v[92:93], 0, 0
	v_pk_mov_b32 v[94:95], 0, 0
	v_pk_mov_b32 v[96:97], 0, 0
	v_pk_mov_b32 v[98:99], 0, 0
	v_pk_mov_b32 v[100:101], 0, 0
	v_pk_mov_b32 v[102:103], 0, 0
	v_pk_mov_b32 v[104:105], 0, 0
	v_pk_mov_b32 v[106:107], 0, 0
	v_pk_mov_b32 v[108:109], 0, 0
	v_pk_mov_b32 v[110:111], 0, 0
	v_pk_mov_b32 v[112:113], 0, 0
	v_pk_mov_b32 v[114:115], 0, 0
	v_pk_mov_b32 v[116:117], 0, 0
	v_pk_mov_b32 v[118:119], 0, 0
	v_pk_mov_b32 v[120:121], 0, 0
	v_pk_mov_b32 v[122:123], 0, 0
	v_pk_mov_b32 v[124:125], 0, 0
	v_pk_mov_b32 v[126:127], 0, 0

; template <class Epi, class Sched, bool ALIGN_EPI = false, bool SP2 = false>
; __device__ __forceinline__ void gemm_phase(PG8_LAS unsigned char* lds, const Gemm g, const Sched& S, const Epi& E, const int wave_) {
;     ...
;         const bool has_next = S.next(ui + 1, nxt);
;         const char* nA = has_next ? (const char*)g.A + (size_t)nxt.pm * tstep : cA; const char* nB = has_next ? (const char*)g.Bt + (size_t)nxt.pn * tstep : cB;
;     ...
;         for (int a = 0; a < 2; ++a)
; #pragma unroll
;             for (int b = 0; b < 2; ++b)
; #pragma unroll
;                 for (int m = 0; m < 4; ++m)
; #pragma unroll
;                     for (int n = 0; n < 2; ++n) acc[a][b][m][n] = (f32x4){0.f, 0.f, 0.f, 0.f};
;         cur = nxt; cA = nA; cB = nB; ++ui;
.LBB0_699:
	s_ashr_i32 s23, s22, 31
	s_lshl_b64 s[24:25], s[22:23], 20
	v_readlane_b32 s26, v248, 25
	v_readlane_b32 s27, v248, 26
	s_add_u32 s24, s26, s24
	s_addc_u32 s25, s27, s25
	s_and_b64 s[26:27], s[6:7], exec
	s_cselect_b32 s23, s25, s35
	s_cselect_b32 s29, s24, s34
	s_ashr_i32 s21, s20, 31
	s_lshl_b64 s[26:27], s[20:21], 20
	s_add_u32 s26, s62, s26
	s_addc_u32 s27, s63, s27
	s_and_b64 s[40:41], s[6:7], exec
	s_cselect_b32 s21, s27, s37
	s_cselect_b32 s31, s26, s36
	s_add_u32 s34, s34, 0x80080
	s_addc_u32 s35, s35, 0
	s_add_u32 s56, s36, 0x100
	v_mov_b32_e32 v0, 0
	s_addc_u32 s57, s37, 0
	s_mov_b32 s58, -2
	v_mov_b32_e32 v1, 0
	v_pk_mov_b32 v[2:3], 0, 0
	v_pk_mov_b32 v[4:5], 0, 0
	v_pk_mov_b32 v[6:7], 0, 0
	v_pk_mov_b32 v[8:9], 0, 0
	v_pk_mov_b32 v[10:11], 0, 0
	v_pk_mov_b32 v[12:13], 0, 0
	v_pk_mov_b32 v[14:15], 0, 0
	v_pk_mov_b32 v[16:17], 0, 0
	v_pk_mov_b32 v[18:19], 0, 0
	v_pk_mov_b32 v[20:21], 0, 0
	v_pk_mov_b32 v[22:23], 0, 0
	v_pk_mov_b32 v[24:25], 0, 0
	v_pk_mov_b32 v[26:27], 0, 0
	v_pk_mov_b32 v[28:29], 0, 0
	v_pk_mov_b32 v[30:31], 0, 0
	v_pk_mov_b32 v[32:33], 0, 0
	v_pk_mov_b32 v[34:35], 0, 0
	v_pk_mov_b32 v[36:37], 0, 0
	v_pk_mov_b32 v[38:39], 0, 0
	v_pk_mov_b32 v[40:41], 0, 0
	v_pk_mov_b32 v[42:43], 0, 0
	v_pk_mov_b32 v[44:45], 0, 0
	v_pk_mov_b32 v[46:47], 0, 0
	v_pk_mov_b32 v[48:49], 0, 0
	v_pk_mov_b32 v[50:51], 0, 0
	v_pk_mov_b32 v[52:53], 0, 0
	v_pk_mov_b32 v[54:55], 0, 0
	v_pk_mov_b32 v[56:57], 0, 0
	v_pk_mov_b32 v[58:59], 0, 0
	v_pk_mov_b32 v[60:61], 0, 0
	v_pk_mov_b32 v[62:63], 0, 0
	v_pk_mov_b32 v[64:65], 0, 0
	v_pk_mov_b32 v[66:67], 0, 0
	v_pk_mov_b32 v[68:69], 0, 0
	v_pk_mov_b32 v[70:71], 0, 0
	v_pk_mov_b32 v[72:73], 0, 0
	v_pk_mov_b32 v[74:75], 0, 0
	v_pk_mov_b32 v[76:77], 0, 0
	v_pk_mov_b32 v[78:79], 0, 0
	v_pk_mov_b32 v[80:81], 0, 0
	v_pk_mov_b32 v[82:83], 0, 0
	v_pk_mov_b32 v[84:85], 0, 0
	v_pk_mov_b32 v[86:87], 0, 0
	v_pk_mov_b32 v[88:89], 0, 0
	v_pk_mov_b32 v[90:91], 0, 0
	v_pk_mov_b32 v[92:93], 0, 0
	v_pk_mov_b32 v[94:95], 0, 0
	v_pk_mov_b32 v[96:97], 0, 0
	v_pk_mov_b32 v[98:99], 0, 0
	v_pk_mov_b32 v[100:101], 0, 0
	v_pk_mov_b32 v[102:103], 0, 0
	v_pk_mov_b32 v[104:105], 0, 0
	v_pk_mov_b32 v[106:107], 0, 0
	v_pk_mov_b32 v[108:109], 0, 0
	v_pk_mov_b32 v[110:111], 0, 0
	v_pk_mov_b32 v[112:113], 0, 0
	v_pk_mov_b32 v[114:115], 0, 0
	v_pk_mov_b32 v[116:117], 0, 0
	v_pk_mov_b32 v[118:119], 0, 0
	v_pk_mov_b32 v[120:121], 0, 0
	v_pk_mov_b32 v[122:123], 0, 0
	v_pk_mov_b32 v[124:125], 0, 0
	v_pk_mov_b32 v[126:127], 0, 0
